# priority raise for waves 4-7 at the start of every phase (GEMM phases keep their own per-block toggles)
# baseline (speedup 1.0000x reference)
.LBB0_75:
	v_readfirstlane_b32 s100, v202
	s_nop 3
	s_lshr_b32 s100, s100, 6
	s_cmp_ge_u32 s100, 4
	s_cbranch_scc0 .Lph_prio_done
	s_setprio 1
